# mixer-B tile loop hand-scheduled (bias in accumulator init, window mask only on outer tiles, fragment prefetch); attnA rescale check threshold 40; unit epilogue row sums by DPP
# speedup vs baseline: 1.0206x; 1.0096x over previous
;     __device__ bool next(int i, Unit& u) const {
;         const long L = (long)i * G + c; if (L >= nwg) return false;
;         int wgid = (int)L; { const int q = nwg / NXCD, r = nwg % NXCD, xcd = wgid % NXCD, off = wgid / NXCD; wgid = (xcd < r ? xcd * (q + 1) : r * (q + 1) + (xcd - r) * q) + off; }
;         const int nig = WGM * nN, gid = wgid / nig, fm = gid * WGM, gsz = (nM - fm) < WGM ? (nM - fm) : WGM;
;         u.pm = fm + ((wgid % nig) % gsz); u.pn = (wgid % nig) / gsz; return true;
;     }
; __device__ __forceinline__ void unitA(LAS char* lds, const gbf* PROJ, const gbf* VT, gbf* Y, const int S, const int tok0, const int h, const int qblk,
;                                       const float lam, const float oml, const gfl* subln, const float kn2a, const float kn2b, const int tid_) {
;     ...
;           const bool chk = frst || !(ew - slope2 * (float)dmin < 7.5f);
.LBB0_120:
	v_readlane_b32 s0, v254, 0
	v_readlane_b32 s1, v254, 1
	s_mul_i32 s0, s1, s0
	s_ashr_i32 s1, s95, 31
	v_writelane_b32 v254, s1, 11
	s_lshr_b32 s1, s1, 29
	s_add_i32 s1, s95, s1
	s_ashr_i32 s11, s1, 3
	s_and_b32 s1, s1, -8
	s_sub_i32 s12, s95, s1
	s_cmpk_lt_i32 s95, 0xf00
	s_cselect_b64 s[2:3], -1, 0
	v_lshrrev_b32_e32 v1, 20, v0
	v_lshrrev_b32_e32 v0, 10, v0
	v_writelane_b32 v254, s2, 12
	s_cmpk_lt_i32 s95, 0x300
	v_or_b32_e32 v0, v0, v1
	s_movk_i32 s1, 0x3ff
	v_writelane_b32 v254, s3, 13
	s_cselect_b64 s[2:3], -1, 0
	v_and_or_b32 v0, v0, s1, v37
	v_writelane_b32 v254, s2, 14
	s_lshl_b32 s1, s95, 9
	s_cmpk_lt_i32 s95, 0x400
	v_writelane_b32 v254, s3, 15
	v_writelane_b32 v254, s1, 16
	s_cselect_b64 s[2:3], -1, 0
	s_lshl_b32 s1, s12, 7
	v_writelane_b32 v254, s2, 17
	s_cmpk_lt_i32 s95, 0x1642
	s_mov_b32 s77, 0
	v_writelane_b32 v254, s3, 18
	s_cselect_b64 s[2:3], -1, 0
	v_writelane_b32 v254, s2, 19
	s_mov_b32 s46, 2.0
	s_mov_b32 s48, 4.0
	v_writelane_b32 v254, s3, 20
	s_mul_i32 s2, s12, 0x2c8
	s_waitcnt lgkmcnt(0)
	s_or_b32 s6, s2, 2
	v_readlane_b32 s2, v254, 2
	v_readlane_b32 s3, v254, 3
	s_load_dword s2, s[2:3], 0xb8
	s_cmp_lt_i32 s12, 0
	s_movk_i32 s3, 0x61
	s_cselect_b32 s3, s3, 0x60
	s_mul_i32 s3, s12, s3
	s_waitcnt lgkmcnt(0)
	s_mul_i32 s0, s0, s2
	s_movk_i32 s2, 0x1e1
	s_cselect_b32 s2, s2, 0x1e0
	v_writelane_b32 v254, s0, 21
	s_mul_i32 s0, s12, 0x81
	s_mul_i32 s2, s12, s2
	s_cselect_b32 s1, s0, s1
	s_add_i32 s2, s2, s11
	s_mul_hi_i32 s0, s2, 0x88888889
	s_add_i32 s0, s0, s2
	s_lshr_b32 s4, s0, 31
	s_ashr_i32 s0, s0, 6
	s_add_i32 s0, s0, s4
	s_mul_i32 s4, s0, 0x78
	s_sub_i32 s2, s2, s4
	s_lshl_b32 s5, s0, 3
	s_bfe_i32 s0, s2, 0x80000
	s_bfe_u32 s0, s0, 0x3000c
	s_add_i32 s4, s2, s0
	s_bfe_i32 s0, s4, 0x80000
	s_and_b32 s4, s4, 0xf8
	s_sub_i32 s2, s2, s4
	s_sext_i32_i16 s7, s0
	s_sext_i32_i8 s2, s2
	s_add_i32 s13, s5, s2
	s_ashr_i32 s2, s7, 3
	v_writelane_b32 v254, s2, 22
	s_add_i32 s2, s3, s11
	s_ashr_i32 s3, s2, 31
	s_lshr_b32 s3, s3, 21
	s_add_i32 s3, s2, s3
	s_ashr_i32 s4, s3, 11
	s_and_b32 s3, s3, 0xfffff800
	s_add_i32 s1, s1, s11
	s_sub_i32 s10, s2, s3
	s_ashr_i32 s2, s1, 31
	s_lshr_b32 s2, s2, 27
	s_add_i32 s2, s1, s2
	s_ashr_i32 s3, s2, 5
	s_and_b32 s2, s2, 0xffe0
	s_sub_i32 s1, s1, s2
	s_lshl_b32 s8, s4, 3
	s_bfe_i32 s2, s1, 0x80000
	s_sub_i32 s4, 3, s8
	s_bfe_u32 s2, s2, 0x3000c
	s_min_u32 s9, s4, 8
	s_add_i32 s4, s1, s2
	s_bfe_i32 s2, s4, 0x80000
	s_and_b32 s4, s4, 0xf8
	s_sub_i32 s1, s1, s4
	s_lshl_b32 s3, s3, 3
	s_sext_i32_i8 s1, s1
	s_sext_i32_i16 s5, s2
	s_add_i32 s1, s3, s1
	s_ashr_i32 s3, s5, 3
	s_lshl_b32 s4, s1, 8
	s_lshr_b32 s2, s5, 3
	v_writelane_b32 v254, s3, 23
	s_ashr_i32 s5, s4, 31
	v_writelane_b32 v254, s1, 24
	s_lshl_b64 s[14:15], s[4:5], 11
	v_writelane_b32 v254, s14, 25
	s_bfe_i64 s[2:3], s[2:3], 0x100000
	s_lshr_b32 s0, s7, 3
	v_writelane_b32 v254, s15, 26
	s_lshl_b64 s[14:15], s[2:3], 18
	s_cmp_lt_i32 s12, 2
	s_mul_i32 s1, s12, 0x2c9
	s_cselect_b32 s1, s1, s6
	s_add_i32 s1, s1, s11
	v_writelane_b32 v254, s14, 27
	s_mul_hi_i32 s5, s1, 0x2e8ba2e9
	s_lshr_b32 s6, s5, 31
	v_writelane_b32 v254, s15, 28
	s_ashr_i32 s5, s5, 5
	v_writelane_b32 v254, s12, 29
	s_add_i32 s5, s5, s6
	v_writelane_b32 v254, s11, 30
	s_lshl_b32 s11, s5, 3
	s_sub_i32 s6, 0x103, s11
	s_min_u32 s12, s6, 8
	s_lshl_b32 s6, s13, 8
	s_ashr_i32 s7, s6, 31
	v_cvt_f32_ubyte0_e32 v2, s9
	s_mulk_i32 s5, 0xb0
	v_writelane_b32 v254, s13, 31
	s_lshl_b64 s[6:7], s[6:7], 11
	v_cvt_f32_i32_e32 v1, s10
	v_rcp_iflag_f32_e32 v3, v2
	s_sub_i32 s5, s1, s5
	v_writelane_b32 v254, s6, 32
	s_bfe_i64 s[0:1], s[0:1], 0x100000
	s_lshl_b64 s[0:1], s[0:1], 19
	v_writelane_b32 v254, s7, 33
	v_writelane_b32 v254, s0, 34
	v_mul_f32_e32 v3, v1, v3
	v_trunc_f32_e32 v3, v3
	v_writelane_b32 v254, s1, 35
	s_lshl_b64 s[0:1], s[2:3], 19
	v_writelane_b32 v254, s0, 36
	v_fma_f32 v1, -v3, v2, v1
	v_cvt_i32_f32_e32 v3, v3
	v_writelane_b32 v254, s1, 37
	s_mul_hi_i32 s0, s4, 0x1600
	v_writelane_b32 v254, s0, 38
	s_ashr_i32 s0, s10, 30
	s_or_b32 s2, s0, 1
	v_cmp_ge_f32_e64 s[0:1], |v1|, v2
	s_and_b64 s[0:1], s[0:1], exec
	s_cselect_b32 s0, s2, 0
	v_readfirstlane_b32 s1, v3
	s_add_i32 s0, s1, s0
	s_sext_i32_i16 s1, s0
	v_writelane_b32 v254, s1, 39
	s_mul_i32 s1, s0, s9
	s_sub_i32 s1, s10, s1
	s_sext_i32_i16 s1, s1
	v_cvt_f32_ubyte0_e32 v2, s12
	s_add_i32 s1, s8, s1
	v_cvt_f32_i32_e32 v1, s5
	v_rcp_iflag_f32_e32 v3, v2
	s_lshl_b32 s2, s1, 8
	s_ashr_i32 s3, s2, 31
	v_writelane_b32 v254, s1, 40
	s_lshl_b64 s[2:3], s[2:3], 11
	v_writelane_b32 v254, s2, 41
	s_bfe_i64 s[0:1], s[0:1], 0x100000
	v_mul_f32_e32 v3, v1, v3
	v_writelane_b32 v254, s3, 42
	s_lshl_b64 s[0:1], s[0:1], 19
	v_trunc_f32_e32 v3, v3
	v_writelane_b32 v254, s0, 43
	v_fma_f32 v1, -v3, v2, v1
	v_cvt_i32_f32_e32 v3, v3
	v_writelane_b32 v254, s1, 44
	s_ashr_i32 s0, s5, 30
	s_or_b32 s2, s0, 1
	v_cmp_ge_f32_e64 s[0:1], |v1|, v2
	s_and_b64 s[0:1], s[0:1], exec
	s_cselect_b32 s0, s2, 0
	v_readfirstlane_b32 s1, v3
	s_add_i32 s0, s1, s0
	s_sext_i32_i16 s1, s0
	s_mul_i32 s0, s0, s12
	s_sub_i32 s0, s5, s0
	s_sext_i32_i16 s0, s0
	v_writelane_b32 v254, s1, 45
	s_add_i32 s0, s11, s0
	v_writelane_b32 v254, s0, 46
	s_add_i32 s0, 0, 0x21000
	v_writelane_b32 v254, s0, 47
	s_add_i32 s0, 0, 0x21004
	v_writelane_b32 v254, s0, 48
	s_add_i32 s0, 0, 0x2400
	v_writelane_b32 v254, s0, 49
	v_cmp_eq_u32_e64 s[0:1], 0, v0
	v_mov_b32_e32 v1, 0
	s_mov_b32 s50, 0x40c00000
	v_writelane_b32 v254, s0, 50
	s_mov_b32 s52, 0x41800000
	s_mov_b32 s54, 0x41900000
	v_writelane_b32 v254, s1, 51
	s_mov_b32 s0, s77
	v_writelane_b32 v254, s0, 52
	s_mov_b32 s56, 0x41a00000
	s_mov_b32 s58, 0x41b00000
	s_mov_b32 s60, 0x42580000
	s_mov_b32 s62, 0x42500000
	s_mov_b32 s64, 0x42480000
	s_mov_b32 s66, 0x42400000
	s_mov_b32 s68, 0x42180000
	s_mov_b32 s70, 0x42100000
	s_mov_b32 s72, 0x42080000
	s_mov_b32 s74, 0x42000000
	v_writelane_b32 v254, s1, 53
	v_mov_b32_e32 v218, 0x358637bd
	v_mov_b32_e32 v219, 0x2000
	v_mov_b32_e32 v222, 1
	v_mov_b32_e32 v223, 0x260
	v_mov_b32_e32 v224, 0x3d4ccccd
	s_mov_b32 s47, 0x40400000
	s_mov_b32 s49, 0x40a00000
	s_mov_b32 s51, 0x40e00000
	s_mov_b32 s53, 0x41880000
	s_mov_b32 s55, 0x41980000
	s_mov_b32 s57, 0x41a80000
	s_mov_b32 s59, 0x41b80000
	s_mov_b32 s61, 0x425c0000
	s_mov_b32 s63, 0x42540000
	s_mov_b32 s65, 0x424c0000
	s_mov_b32 s67, 0x42440000
	s_mov_b32 s69, 0x421c0000
	s_mov_b32 s71, 0x42140000
	s_mov_b32 s73, 0x420c0000
	v_mov_b32_e32 v225, 0xc0135761
	v_mov_b32_e32 v228, 0x1e00
	v_mov_b32_e32 v229, 0xf149f2ca
	v_mov_b64_e32 v[188:189], 0x400
	v_mov_b64_e32 v[190:191], 0x3ff
	v_mov_b64_e32 v[226:227], 0x1642
	v_mov_b32_e32 v230, 0x200
	v_mov_b64_e32 v[220:221], 0x1641
	s_mov_b32 s75, 0x42040000
	v_mov_b32_e32 v252, v1
	v_mov_b32_e32 v253, v1
	s_mov_b32 s18, 0x41000000
	s_mov_b32 s14, 0x42200000
	s_add_i32 s15, 0, 0x21010
	s_mov_b32 s3, 0x43000000
	s_mov_b64 s[4:5], -1
	s_mov_b64 s[78:79], 0x80
	s_mov_b64 s[80:81], 0x400
	v_writelane_b32 v254, s95, 54
	s_branch .LBB0_122

; __device__ __forceinline__ unsigned cvt_pk_bf16(float lo, float hi) { unsigned r; asm("v_cvt_pk_bf16_f32 %0, %1, %2" : "=v"(r) : "v"(lo), "v"(hi)); return r; }
; __device__ __forceinline__ float sum_row32(float v) { v += swz_xor<1>(v); v += swz_xor<2>(v); v += swz_xor<4>(v); v += swz_xor<8>(v); v += swz_xor<16>(v); return v; }
; __device__ __forceinline__ int crow(int r, int hi) { return (r & 3) + 8 * (r >> 2) + 4 * hi; }
; __device__ __forceinline__ void unitA(LAS char* lds, const gbf* PROJ, const gbf* VT, gbf* Y, const int S, const int tok0, const int h, const int qblk,
;                                       const float lam, const float oml, const gfl* subln, const float kn2a, const float kn2b, const int tid_) {
;     ...
;         for (int r = 0; r < 16; ++r) {
;             float ss = 0.f;
; #pragma unroll
;             for (int d = 0; d < 4; ++d) { const float v = o[d][r] * invr[r] - X[(d * 16 + r) * 64 + lane]; o[d][r] = v; ss += v * v; }
;             ss = sum_row32(ss);
;             const float rstd = __builtin_amdgcn_rsqf(ss * (1.f / 128.f) + EPS);
;             gbf* yp = Y + (size_t)(tok0 + q0 + crow(r, hi)) * DM + h * 128 + r32e;
; #pragma unroll
;             for (int d = 0; d < 4; ++d) yp[d * 32] = (bf16_t)(cvt_pk_bf16(o[d][r] * rstd * sub[d], 0.f) & 0xffffu);
;         }
.LBB0_425:
	s_andn2_b64 vcc, exec, s[10:11]
	s_waitcnt vmcnt(0) lgkmcnt(0)
	s_barrier
	s_cbranch_vccnz .LBB0_358
	v_readlane_b32 s4, v255, 1
	v_readlane_b32 s5, v255, 2
	v_ashrrev_i32_e32 v179, 31, v178
	ds_read2st64_b32 v[90:91], v89 offset1:1
	ds_read2st64_b32 v[92:93], v89 offset0:16 offset1:17
	ds_read2st64_b32 v[94:95], v89 offset0:32 offset1:33
	ds_read2st64_b32 v[96:97], v89 offset0:48 offset1:49
	v_lshl_add_u64 v[82:83], v[178:179], 2, s[4:5]
	global_load_dword v0, v[82:83], off
	global_load_dword v84, v[82:83], off offset:128
	s_waitcnt lgkmcnt(2)
	v_fma_f32 v18, v18, v78, -v92
	v_fma_f32 v2, v2, v78, -v90
	s_waitcnt lgkmcnt(1)
	v_fma_f32 v34, v34, v78, -v94
	s_waitcnt lgkmcnt(0)
	v_fma_f32 v50, v50, v78, -v96
	s_lshl_b32 s0, s0, 1
	v_readlane_b32 s2, v254, 61
	s_add_u32 s4, s2, s0
	v_readlane_b32 s0, v254, 62
	s_addc_u32 s5, s0, 0
	v_fma_f32 v19, v19, v79, -v93
	s_waitcnt vmcnt(1)
	v_mul_f32_e32 v0, v207, v0
	s_waitcnt vmcnt(0)
	v_mul_f32_e32 v86, v207, v84
	global_load_dword v84, v[82:83], off offset:256
	s_waitcnt vmcnt(0)
	v_mul_f32_e32 v87, v207, v84
	global_load_dword v82, v[82:83], off offset:384
	v_mul_f32_e32 v83, v18, v18
	v_fmac_f32_e32 v83, v2, v2
	v_fmac_f32_e32 v83, v34, v34
	v_fmac_f32_e32 v83, v50, v50
	v_lshl_add_u64 v[84:85], v[178:179], 1, s[4:5]
	s_nop 1
	v_add_f32_dpp v78, v83, v83 row_ror:1 row_mask:0xf bank_mask:0xf
	s_nop 1
	v_add_f32_dpp v78, v78, v78 row_ror:2 row_mask:0xf bank_mask:0xf
	s_nop 1
	v_add_f32_dpp v78, v78, v78 row_ror:4 row_mask:0xf bank_mask:0xf
	s_nop 1
	v_add_f32_dpp v78, v78, v78 row_ror:8 row_mask:0xf bank_mask:0xf
	ds_swizzle_b32 v83, v78 offset:swizzle(SWAP,16)
	s_waitcnt lgkmcnt(0)
	v_add_f32_e32 v78, v78, v83
	v_fmamk_f32 v78, v78, 0x3c000000, v218
	v_rsq_f32_e32 v78, v78
	s_waitcnt vmcnt(0)
	v_mul_f32_e32 v88, v207, v82
	v_lshl_or_b32 v82, v210, 2, s86
	v_ashrrev_i32_e32 v83, 31, v82
	v_mul_f32_e32 v2, v2, v78
	v_lshlrev_b64 v[98:99], 11, v[82:83]
	v_mul_f32_e32 v2, v0, v2
	v_lshl_add_u64 v[98:99], v[84:85], 0, v[98:99]
	v_cvt_pk_bf16_f32 v2, v2, v1
	global_store_short v[98:99], v2, off
	v_mul_f32_e32 v2, v18, v78
	v_mul_f32_e32 v2, v86, v2
	v_cvt_pk_bf16_f32 v2, v2, v1
	global_store_short v[98:99], v2, off offset:64
	v_mul_f32_e32 v2, v34, v78
	v_mul_f32_e32 v2, v87, v2
	v_cvt_pk_bf16_f32 v2, v2, v1
	global_store_short v[98:99], v2, off offset:128
	v_mul_f32_e32 v2, v50, v78
	v_mul_f32_e32 v2, v88, v2
	v_cvt_pk_bf16_f32 v2, v2, v1
	global_store_short v[98:99], v2, off offset:192
	v_fma_f32 v18, v3, v79, -v91
	v_mul_f32_e32 v2, v19, v19
	v_fmac_f32_e32 v2, v18, v18
	v_fma_f32 v34, v35, v79, -v95
	v_fmac_f32_e32 v2, v34, v34
	v_fma_f32 v35, v51, v79, -v97
	v_fmac_f32_e32 v2, v35, v35
	v_or_b32_e32 v78, 2, v82
	v_ashrrev_i32_e32 v79, 31, v78
	v_lshlrev_b64 v[78:79], 11, v[78:79]
	v_lshl_add_u64 v[78:79], v[84:85], 0, v[78:79]
	s_nop 1
	v_add_f32_dpp v2, v2, v2 row_ror:1 row_mask:0xf bank_mask:0xf
	s_nop 1
	v_add_f32_dpp v2, v2, v2 row_ror:2 row_mask:0xf bank_mask:0xf
	s_nop 1
	v_add_f32_dpp v2, v2, v2 row_ror:4 row_mask:0xf bank_mask:0xf
	s_nop 1
	v_add_f32_dpp v2, v2, v2 row_ror:8 row_mask:0xf bank_mask:0xf
	ds_swizzle_b32 v3, v2 offset:swizzle(SWAP,16)
	s_waitcnt lgkmcnt(0)
	v_add_f32_e32 v2, v2, v3
	v_fmamk_f32 v2, v2, 0x3c000000, v218
	v_rsq_f32_e32 v50, v2
	v_or_b32_e32 v2, 1, v82
	v_ashrrev_i32_e32 v3, 31, v2
	v_lshlrev_b64 v[2:3], 11, v[2:3]
	v_mul_f32_e32 v18, v18, v50
	v_mul_f32_e32 v18, v0, v18
	v_lshl_add_u64 v[2:3], v[84:85], 0, v[2:3]
	v_cvt_pk_bf16_f32 v18, v18, v1
	global_store_short v[2:3], v18, off
	v_mul_f32_e32 v18, v19, v50
	v_mul_f32_e32 v18, v86, v18
	v_cvt_pk_bf16_f32 v18, v18, v1
	global_store_short v[2:3], v18, off offset:64
	v_mul_f32_e32 v18, v34, v50
	v_mul_f32_e32 v18, v87, v18
	v_cvt_pk_bf16_f32 v18, v18, v1
	global_store_short v[2:3], v18, off offset:128
	v_mul_f32_e32 v18, v35, v50
	v_mul_f32_e32 v18, v88, v18
	v_cvt_pk_bf16_f32 v18, v18, v1
	global_store_short v[2:3], v18, off offset:192
	ds_read2st64_b32 v[2:3], v89 offset0:2 offset1:3
	ds_read2st64_b32 v[18:19], v89 offset0:18 offset1:19
	ds_read2st64_b32 v[34:35], v89 offset0:34 offset1:35
	ds_read2st64_b32 v[50:51], v89 offset0:50 offset1:51
	s_waitcnt lgkmcnt(3)
	v_fma_f32 v2, v4, v80, -v2
	s_waitcnt lgkmcnt(2)
	v_fma_f32 v4, v20, v80, -v18
	v_mul_f32_e32 v18, v4, v4
	v_fmac_f32_e32 v18, v2, v2
	s_waitcnt lgkmcnt(1)
	v_fma_f32 v20, v36, v80, -v34
	v_fmac_f32_e32 v18, v20, v20
	s_waitcnt lgkmcnt(0)
	v_fma_f32 v34, v52, v80, -v50
	v_fmac_f32_e32 v18, v34, v34
	s_nop 1
	v_add_f32_dpp v18, v18, v18 row_ror:1 row_mask:0xf bank_mask:0xf
	s_nop 1
	v_add_f32_dpp v18, v18, v18 row_ror:2 row_mask:0xf bank_mask:0xf
	s_nop 1
	v_add_f32_dpp v18, v18, v18 row_ror:4 row_mask:0xf bank_mask:0xf
	s_nop 1
	v_add_f32_dpp v18, v18, v18 row_ror:8 row_mask:0xf bank_mask:0xf
	ds_swizzle_b32 v36, v18 offset:swizzle(SWAP,16)
	s_waitcnt lgkmcnt(0)
	v_add_f32_e32 v18, v18, v36
	v_fmamk_f32 v18, v18, 0x3c000000, v218
	v_rsq_f32_e32 v18, v18
	s_nop 0
	v_mul_f32_e32 v2, v2, v18
	v_mul_f32_e32 v2, v0, v2
	v_cvt_pk_bf16_f32 v2, v2, v1
	global_store_short v[78:79], v2, off
	v_mul_f32_e32 v2, v4, v18
	v_mul_f32_e32 v2, v86, v2
	v_cvt_pk_bf16_f32 v2, v2, v1
	global_store_short v[78:79], v2, off offset:64
	v_mul_f32_e32 v2, v20, v18
	v_mul_f32_e32 v2, v87, v2
	v_cvt_pk_bf16_f32 v2, v2, v1
	global_store_short v[78:79], v2, off offset:128
	v_mul_f32_e32 v2, v34, v18
	v_mul_f32_e32 v2, v88, v2
	v_cvt_pk_bf16_f32 v2, v2, v1
	v_fma_f32 v4, v5, v81, -v3
	v_fma_f32 v5, v21, v81, -v19
	global_store_short v[78:79], v2, off offset:192
	v_mul_f32_e32 v2, v5, v5
	v_fmac_f32_e32 v2, v4, v4
	v_fma_f32 v18, v37, v81, -v35
	v_fmac_f32_e32 v2, v18, v18
	v_fma_f32 v19, v53, v81, -v51
	v_fmac_f32_e32 v2, v19, v19
	v_or_b32_e32 v34, 8, v82
	v_ashrrev_i32_e32 v35, 31, v34
	v_lshlrev_b64 v[34:35], 11, v[34:35]
	v_lshl_add_u64 v[34:35], v[84:85], 0, v[34:35]
	s_nop 1
	v_add_f32_dpp v2, v2, v2 row_ror:1 row_mask:0xf bank_mask:0xf
	s_nop 1
	v_add_f32_dpp v2, v2, v2 row_ror:2 row_mask:0xf bank_mask:0xf
	s_nop 1
	v_add_f32_dpp v2, v2, v2 row_ror:4 row_mask:0xf bank_mask:0xf
	s_nop 1
	v_add_f32_dpp v2, v2, v2 row_ror:8 row_mask:0xf bank_mask:0xf
	ds_swizzle_b32 v3, v2 offset:swizzle(SWAP,16)
	s_waitcnt lgkmcnt(0)
; __device__ __forceinline__ unsigned cvt_pk_bf16(float lo, float hi) { unsigned r; asm("v_cvt_pk_bf16_f32 %0, %1, %2" : "=v"(r) : "v"(lo), "v"(hi)); return r; }
; __device__ __forceinline__ float sum_row32(float v) { v += swz_xor<1>(v); v += swz_xor<2>(v); v += swz_xor<4>(v); v += swz_xor<8>(v); v += swz_xor<16>(v); return v; }
; __device__ __forceinline__ int crow(int r, int hi) { return (r & 3) + 8 * (r >> 2) + 4 * hi; }
; __device__ __forceinline__ void unitA(LAS char* lds, const gbf* PROJ, const gbf* VT, gbf* Y, const int S, const int tok0, const int h, const int qblk,
;                                       const float lam, const float oml, const gfl* subln, const float kn2a, const float kn2b, const int tid_) {
;     ...
;         for (int r = 0; r < 16; ++r) {
;             float ss = 0.f;
; #pragma unroll
;             for (int d = 0; d < 4; ++d) { const float v = o[d][r] * invr[r] - X[(d * 16 + r) * 64 + lane]; o[d][r] = v; ss += v * v; }
;             ss = sum_row32(ss);
;             const float rstd = __builtin_amdgcn_rsqf(ss * (1.f / 128.f) + EPS);
;             gbf* yp = Y + (size_t)(tok0 + q0 + crow(r, hi)) * DM + h * 128 + r32e;
; #pragma unroll
;             for (int d = 0; d < 4; ++d) yp[d * 32] = (bf16_t)(cvt_pk_bf16(o[d][r] * rstd * sub[d], 0.f) & 0xffffu);
;         }
	v_add_f32_e32 v2, v2, v3
	v_fmamk_f32 v2, v2, 0x3c000000, v218
	v_rsq_f32_e32 v20, v2
	v_or_b32_e32 v2, 3, v82
	v_ashrrev_i32_e32 v3, 31, v2
	v_lshlrev_b64 v[2:3], 11, v[2:3]
	v_mul_f32_e32 v4, v4, v20
	v_mul_f32_e32 v4, v0, v4
	v_lshl_add_u64 v[2:3], v[84:85], 0, v[2:3]
	v_cvt_pk_bf16_f32 v4, v4, v1
	global_store_short v[2:3], v4, off
	v_mul_f32_e32 v4, v5, v20
	v_mul_f32_e32 v4, v86, v4
	v_cvt_pk_bf16_f32 v4, v4, v1
	global_store_short v[2:3], v4, off offset:64
	v_mul_f32_e32 v4, v18, v20
	v_mul_f32_e32 v4, v87, v4
	v_cvt_pk_bf16_f32 v4, v4, v1
	global_store_short v[2:3], v4, off offset:128
	v_mul_f32_e32 v4, v19, v20
	v_mul_f32_e32 v4, v88, v4
	v_cvt_pk_bf16_f32 v4, v4, v1
	global_store_short v[2:3], v4, off offset:192
	ds_read2st64_b32 v[2:3], v89 offset0:4 offset1:5
	ds_read2st64_b32 v[4:5], v89 offset0:20 offset1:21
	ds_read2st64_b32 v[18:19], v89 offset0:36 offset1:37
	ds_read2st64_b32 v[20:21], v89 offset0:52 offset1:53
	s_waitcnt lgkmcnt(3)
	v_fma_f32 v2, v6, v74, -v2
	s_waitcnt lgkmcnt(2)
	v_fma_f32 v4, v22, v74, -v4
	v_mul_f32_e32 v6, v4, v4
	v_fmac_f32_e32 v6, v2, v2
	s_waitcnt lgkmcnt(1)
	v_fma_f32 v18, v38, v74, -v18
	v_fmac_f32_e32 v6, v18, v18
	s_waitcnt lgkmcnt(0)
	v_fma_f32 v20, v54, v74, -v20
	v_fmac_f32_e32 v6, v20, v20
	v_fma_f32 v5, v23, v75, -v5
	s_nop 1
	v_add_f32_dpp v6, v6, v6 row_ror:1 row_mask:0xf bank_mask:0xf
	s_nop 1
	v_add_f32_dpp v6, v6, v6 row_ror:2 row_mask:0xf bank_mask:0xf
	s_nop 1
	v_add_f32_dpp v6, v6, v6 row_ror:4 row_mask:0xf bank_mask:0xf
	s_nop 1
	v_add_f32_dpp v6, v6, v6 row_ror:8 row_mask:0xf bank_mask:0xf
	ds_swizzle_b32 v22, v6 offset:swizzle(SWAP,16)
	s_waitcnt lgkmcnt(0)
	v_add_f32_e32 v6, v6, v22
	v_fmamk_f32 v6, v6, 0x3c000000, v218
	v_rsq_f32_e32 v6, v6
	s_nop 0
	v_mul_f32_e32 v2, v2, v6
	v_mul_f32_e32 v2, v0, v2
	v_cvt_pk_bf16_f32 v2, v2, v1
	global_store_short v[34:35], v2, off
	v_mul_f32_e32 v2, v4, v6
	v_mul_f32_e32 v2, v86, v2
	v_cvt_pk_bf16_f32 v2, v2, v1
	global_store_short v[34:35], v2, off offset:64
	v_mul_f32_e32 v2, v18, v6
	v_mul_f32_e32 v2, v87, v2
	v_cvt_pk_bf16_f32 v2, v2, v1
	global_store_short v[34:35], v2, off offset:128
	v_mul_f32_e32 v2, v20, v6
	v_mul_f32_e32 v2, v88, v2
	v_cvt_pk_bf16_f32 v2, v2, v1
	global_store_short v[34:35], v2, off offset:192
	v_fma_f32 v4, v7, v75, -v3
	v_mul_f32_e32 v2, v5, v5
	v_fmac_f32_e32 v2, v4, v4
	v_fma_f32 v6, v39, v75, -v19
	v_fmac_f32_e32 v2, v6, v6
	v_fma_f32 v7, v55, v75, -v21
	v_fmac_f32_e32 v2, v7, v7
	s_nop 1
	v_add_f32_dpp v2, v2, v2 row_ror:1 row_mask:0xf bank_mask:0xf
	s_nop 1
	v_add_f32_dpp v2, v2, v2 row_ror:2 row_mask:0xf bank_mask:0xf
	s_nop 1
	v_add_f32_dpp v2, v2, v2 row_ror:4 row_mask:0xf bank_mask:0xf
	s_nop 1
	v_add_f32_dpp v2, v2, v2 row_ror:8 row_mask:0xf bank_mask:0xf
	ds_swizzle_b32 v3, v2 offset:swizzle(SWAP,16)
	s_waitcnt lgkmcnt(0)
	v_add_f32_e32 v2, v2, v3
	v_fmamk_f32 v2, v2, 0x3c000000, v218
	v_rsq_f32_e32 v18, v2
	v_or_b32_e32 v2, 9, v82
	v_ashrrev_i32_e32 v3, 31, v2
	v_lshlrev_b64 v[2:3], 11, v[2:3]
	v_mul_f32_e32 v4, v4, v18
	v_mul_f32_e32 v4, v0, v4
	v_lshl_add_u64 v[2:3], v[84:85], 0, v[2:3]
	v_cvt_pk_bf16_f32 v4, v4, v1
	global_store_short v[2:3], v4, off
	v_mul_f32_e32 v4, v5, v18
	v_mul_f32_e32 v4, v86, v4
	v_cvt_pk_bf16_f32 v4, v4, v1
	global_store_short v[2:3], v4, off offset:64
	v_mul_f32_e32 v4, v6, v18
	v_mul_f32_e32 v4, v87, v4
	v_cvt_pk_bf16_f32 v4, v4, v1
	global_store_short v[2:3], v4, off offset:128
	v_mul_f32_e32 v4, v7, v18
	v_mul_f32_e32 v4, v88, v4
	v_cvt_pk_bf16_f32 v4, v4, v1
	global_store_short v[2:3], v4, off offset:192
	ds_read2st64_b32 v[2:3], v89 offset0:6 offset1:7
	ds_read2st64_b32 v[4:5], v89 offset0:22 offset1:23
	ds_read2st64_b32 v[6:7], v89 offset0:38 offset1:39
	ds_read2st64_b32 v[18:19], v89 offset0:54 offset1:55
	s_waitcnt lgkmcnt(3)
	v_fma_f32 v2, v8, v76, -v2
	s_waitcnt lgkmcnt(2)
	v_fma_f32 v4, v24, v76, -v4
	v_mul_f32_e32 v8, v4, v4
	v_fmac_f32_e32 v8, v2, v2
	s_waitcnt lgkmcnt(1)
	v_fma_f32 v6, v40, v76, -v6
	v_fmac_f32_e32 v8, v6, v6
	s_waitcnt lgkmcnt(0)
	v_fma_f32 v18, v56, v76, -v18
	v_fmac_f32_e32 v8, v18, v18
	v_fma_f32 v5, v25, v77, -v5
	s_nop 1
	v_add_f32_dpp v8, v8, v8 row_ror:1 row_mask:0xf bank_mask:0xf
	s_nop 1
	v_add_f32_dpp v8, v8, v8 row_ror:2 row_mask:0xf bank_mask:0xf
	s_nop 1
	v_add_f32_dpp v8, v8, v8 row_ror:4 row_mask:0xf bank_mask:0xf
	s_nop 1
	v_add_f32_dpp v8, v8, v8 row_ror:8 row_mask:0xf bank_mask:0xf
	ds_swizzle_b32 v20, v8 offset:swizzle(SWAP,16)
	s_waitcnt lgkmcnt(0)
	v_add_f32_e32 v8, v8, v20
	v_fmamk_f32 v8, v8, 0x3c000000, v218
	v_rsq_f32_e32 v8, v8
	v_or_b32_e32 v20, 10, v82
	v_ashrrev_i32_e32 v21, 31, v20
	v_lshlrev_b64 v[20:21], 11, v[20:21]
	v_mul_f32_e32 v2, v2, v8
	v_mul_f32_e32 v2, v0, v2
	v_lshl_add_u64 v[20:21], v[84:85], 0, v[20:21]
	v_cvt_pk_bf16_f32 v2, v2, v1
	global_store_short v[20:21], v2, off
	v_mul_f32_e32 v2, v4, v8
	v_mul_f32_e32 v2, v86, v2
	v_cvt_pk_bf16_f32 v2, v2, v1
	global_store_short v[20:21], v2, off offset:64
	v_mul_f32_e32 v2, v6, v8
	v_mul_f32_e32 v2, v87, v2
	v_cvt_pk_bf16_f32 v2, v2, v1
	global_store_short v[20:21], v2, off offset:128
	v_mul_f32_e32 v2, v18, v8
	v_mul_f32_e32 v2, v88, v2
	v_cvt_pk_bf16_f32 v2, v2, v1
	global_store_short v[20:21], v2, off offset:192
	v_fma_f32 v4, v9, v77, -v3
	v_mul_f32_e32 v2, v5, v5
	v_fmac_f32_e32 v2, v4, v4
	v_fma_f32 v6, v41, v77, -v7
	v_fmac_f32_e32 v2, v6, v6
	v_fma_f32 v7, v57, v77, -v19
	v_fmac_f32_e32 v2, v7, v7
	s_nop 1
	v_add_f32_dpp v2, v2, v2 row_ror:1 row_mask:0xf bank_mask:0xf
	s_nop 1
	v_add_f32_dpp v2, v2, v2 row_ror:2 row_mask:0xf bank_mask:0xf
	s_nop 1
	v_add_f32_dpp v2, v2, v2 row_ror:4 row_mask:0xf bank_mask:0xf
	s_nop 1
	v_add_f32_dpp v2, v2, v2 row_ror:8 row_mask:0xf bank_mask:0xf
	ds_swizzle_b32 v3, v2 offset:swizzle(SWAP,16)
	s_waitcnt lgkmcnt(0)
; __device__ __forceinline__ unsigned cvt_pk_bf16(float lo, float hi) { unsigned r; asm("v_cvt_pk_bf16_f32 %0, %1, %2" : "=v"(r) : "v"(lo), "v"(hi)); return r; }
; __device__ __forceinline__ float sum_row32(float v) { v += swz_xor<1>(v); v += swz_xor<2>(v); v += swz_xor<4>(v); v += swz_xor<8>(v); v += swz_xor<16>(v); return v; }
; __device__ __forceinline__ int crow(int r, int hi) { return (r & 3) + 8 * (r >> 2) + 4 * hi; }
; __device__ __forceinline__ void unitA(LAS char* lds, const gbf* PROJ, const gbf* VT, gbf* Y, const int S, const int tok0, const int h, const int qblk,
;                                       const float lam, const float oml, const gfl* subln, const float kn2a, const float kn2b, const int tid_) {
;     ...
;         for (int r = 0; r < 16; ++r) {
;             float ss = 0.f;
; #pragma unroll
;             for (int d = 0; d < 4; ++d) { const float v = o[d][r] * invr[r] - X[(d * 16 + r) * 64 + lane]; o[d][r] = v; ss += v * v; }
;             ss = sum_row32(ss);
;             const float rstd = __builtin_amdgcn_rsqf(ss * (1.f / 128.f) + EPS);
;             gbf* yp = Y + (size_t)(tok0 + q0 + crow(r, hi)) * DM + h * 128 + r32e;
; #pragma unroll
;             for (int d = 0; d < 4; ++d) yp[d * 32] = (bf16_t)(cvt_pk_bf16(o[d][r] * rstd * sub[d], 0.f) & 0xffffu);
;         }
	v_add_f32_e32 v2, v2, v3
	v_fmamk_f32 v2, v2, 0x3c000000, v218
	v_rsq_f32_e32 v8, v2
	v_or_b32_e32 v2, 11, v82
	v_ashrrev_i32_e32 v3, 31, v2
	v_lshlrev_b64 v[2:3], 11, v[2:3]
	v_mul_f32_e32 v4, v4, v8
	v_mul_f32_e32 v4, v0, v4
	v_lshl_add_u64 v[2:3], v[84:85], 0, v[2:3]
	v_cvt_pk_bf16_f32 v4, v4, v1
	global_store_short v[2:3], v4, off
	v_mul_f32_e32 v4, v5, v8
	v_mul_f32_e32 v4, v86, v4
	v_cvt_pk_bf16_f32 v4, v4, v1
	global_store_short v[2:3], v4, off offset:64
	v_mul_f32_e32 v4, v6, v8
	v_mul_f32_e32 v4, v87, v4
	v_cvt_pk_bf16_f32 v4, v4, v1
	global_store_short v[2:3], v4, off offset:128
	v_mul_f32_e32 v4, v7, v8
	v_mul_f32_e32 v4, v88, v4
	v_cvt_pk_bf16_f32 v4, v4, v1
	global_store_short v[2:3], v4, off offset:192
	ds_read2st64_b32 v[2:3], v89 offset0:8 offset1:9
	ds_read2st64_b32 v[4:5], v89 offset0:24 offset1:25
	ds_read2st64_b32 v[6:7], v89 offset0:40 offset1:41
	ds_read2st64_b32 v[8:9], v89 offset0:56 offset1:57
	s_waitcnt lgkmcnt(3)
	v_fma_f32 v2, v10, v70, -v2
	s_waitcnt lgkmcnt(2)
	v_fma_f32 v4, v26, v70, -v4
	v_mul_f32_e32 v10, v4, v4
	v_fmac_f32_e32 v10, v2, v2
	s_waitcnt lgkmcnt(1)
	v_fma_f32 v6, v42, v70, -v6
	v_fmac_f32_e32 v10, v6, v6
	s_waitcnt lgkmcnt(0)
	v_fma_f32 v8, v58, v70, -v8
	v_fmac_f32_e32 v10, v8, v8
	v_fma_f32 v5, v27, v71, -v5
	s_nop 1
	v_add_f32_dpp v10, v10, v10 row_ror:1 row_mask:0xf bank_mask:0xf
	s_nop 1
	v_add_f32_dpp v10, v10, v10 row_ror:2 row_mask:0xf bank_mask:0xf
	s_nop 1
	v_add_f32_dpp v10, v10, v10 row_ror:4 row_mask:0xf bank_mask:0xf
	s_nop 1
	v_add_f32_dpp v10, v10, v10 row_ror:8 row_mask:0xf bank_mask:0xf
	ds_swizzle_b32 v18, v10 offset:swizzle(SWAP,16)
	s_waitcnt lgkmcnt(0)
	v_add_f32_e32 v10, v10, v18
	v_fmamk_f32 v10, v10, 0x3c000000, v218
	v_rsq_f32_e32 v10, v10
	v_or_b32_e32 v18, 16, v82
	v_ashrrev_i32_e32 v19, 31, v18
	v_lshlrev_b64 v[18:19], 11, v[18:19]
	v_mul_f32_e32 v2, v2, v10
	v_mul_f32_e32 v2, v0, v2
	v_lshl_add_u64 v[18:19], v[84:85], 0, v[18:19]
	v_cvt_pk_bf16_f32 v2, v2, v1
	global_store_short v[18:19], v2, off
	v_mul_f32_e32 v2, v4, v10
	v_mul_f32_e32 v2, v86, v2
	v_cvt_pk_bf16_f32 v2, v2, v1
	global_store_short v[18:19], v2, off offset:64
	v_mul_f32_e32 v2, v6, v10
	v_mul_f32_e32 v2, v87, v2
	v_cvt_pk_bf16_f32 v2, v2, v1
	global_store_short v[18:19], v2, off offset:128
	v_mul_f32_e32 v2, v8, v10
	v_mul_f32_e32 v2, v88, v2
	v_cvt_pk_bf16_f32 v2, v2, v1
	global_store_short v[18:19], v2, off offset:192
	v_fma_f32 v4, v11, v71, -v3
	v_mul_f32_e32 v2, v5, v5
	v_fmac_f32_e32 v2, v4, v4
	v_fma_f32 v6, v43, v71, -v7
	v_fmac_f32_e32 v2, v6, v6
	v_fma_f32 v7, v59, v71, -v9
	v_fmac_f32_e32 v2, v7, v7
	s_nop 1
	v_add_f32_dpp v2, v2, v2 row_ror:1 row_mask:0xf bank_mask:0xf
	s_nop 1
	v_add_f32_dpp v2, v2, v2 row_ror:2 row_mask:0xf bank_mask:0xf
	s_nop 1
	v_add_f32_dpp v2, v2, v2 row_ror:4 row_mask:0xf bank_mask:0xf
	s_nop 1
	v_add_f32_dpp v2, v2, v2 row_ror:8 row_mask:0xf bank_mask:0xf
	ds_swizzle_b32 v3, v2 offset:swizzle(SWAP,16)
	s_waitcnt lgkmcnt(0)
	v_add_f32_e32 v2, v2, v3
	v_fmamk_f32 v2, v2, 0x3c000000, v218
	v_rsq_f32_e32 v8, v2
	v_or_b32_e32 v2, 17, v82
	v_ashrrev_i32_e32 v3, 31, v2
	v_lshlrev_b64 v[2:3], 11, v[2:3]
	v_mul_f32_e32 v4, v4, v8
	v_mul_f32_e32 v4, v0, v4
	v_lshl_add_u64 v[2:3], v[84:85], 0, v[2:3]
	v_cvt_pk_bf16_f32 v4, v4, v1
	global_store_short v[2:3], v4, off
	v_mul_f32_e32 v4, v5, v8
	v_mul_f32_e32 v4, v86, v4
	v_cvt_pk_bf16_f32 v4, v4, v1
	global_store_short v[2:3], v4, off offset:64
	v_mul_f32_e32 v4, v6, v8
	v_mul_f32_e32 v4, v87, v4
	v_cvt_pk_bf16_f32 v4, v4, v1
	global_store_short v[2:3], v4, off offset:128
	v_mul_f32_e32 v4, v7, v8
	v_mul_f32_e32 v4, v88, v4
	v_cvt_pk_bf16_f32 v4, v4, v1
	global_store_short v[2:3], v4, off offset:192
	ds_read2st64_b32 v[2:3], v89 offset0:10 offset1:11
	ds_read2st64_b32 v[4:5], v89 offset0:26 offset1:27
	ds_read2st64_b32 v[6:7], v89 offset0:42 offset1:43
	ds_read2st64_b32 v[8:9], v89 offset0:58 offset1:59
	s_waitcnt lgkmcnt(3)
	v_fma_f32 v2, v12, v72, -v2
	s_waitcnt lgkmcnt(2)
	v_fma_f32 v4, v28, v72, -v4
	v_mul_f32_e32 v10, v4, v4
	v_fmac_f32_e32 v10, v2, v2
	s_waitcnt lgkmcnt(1)
	v_fma_f32 v6, v44, v72, -v6
	v_fmac_f32_e32 v10, v6, v6
	s_waitcnt lgkmcnt(0)
	v_fma_f32 v8, v60, v72, -v8
	v_fmac_f32_e32 v10, v8, v8
	v_fma_f32 v5, v29, v73, -v5
	s_nop 1
	v_add_f32_dpp v10, v10, v10 row_ror:1 row_mask:0xf bank_mask:0xf
	s_nop 1
	v_add_f32_dpp v10, v10, v10 row_ror:2 row_mask:0xf bank_mask:0xf
	s_nop 1
	v_add_f32_dpp v10, v10, v10 row_ror:4 row_mask:0xf bank_mask:0xf
	s_nop 1
	v_add_f32_dpp v10, v10, v10 row_ror:8 row_mask:0xf bank_mask:0xf
	ds_swizzle_b32 v11, v10 offset:swizzle(SWAP,16)
	s_waitcnt lgkmcnt(0)
	v_add_f32_e32 v10, v10, v11
	v_fmamk_f32 v10, v10, 0x3c000000, v218
	v_rsq_f32_e32 v12, v10
	v_or_b32_e32 v10, 18, v82
	v_ashrrev_i32_e32 v11, 31, v10
	v_lshlrev_b64 v[10:11], 11, v[10:11]
	v_mul_f32_e32 v2, v2, v12
	v_mul_f32_e32 v2, v0, v2
	v_lshl_add_u64 v[10:11], v[84:85], 0, v[10:11]
	v_cvt_pk_bf16_f32 v2, v2, v1
	global_store_short v[10:11], v2, off
	v_mul_f32_e32 v2, v4, v12
	v_mul_f32_e32 v2, v86, v2
	v_cvt_pk_bf16_f32 v2, v2, v1
	global_store_short v[10:11], v2, off offset:64
	v_mul_f32_e32 v2, v6, v12
	v_mul_f32_e32 v2, v87, v2
	v_cvt_pk_bf16_f32 v2, v2, v1
	global_store_short v[10:11], v2, off offset:128
	v_mul_f32_e32 v2, v8, v12
	v_mul_f32_e32 v2, v88, v2
	v_cvt_pk_bf16_f32 v2, v2, v1
	global_store_short v[10:11], v2, off offset:192
	v_fma_f32 v4, v13, v73, -v3
	v_mul_f32_e32 v2, v5, v5
	v_fmac_f32_e32 v2, v4, v4
	v_fma_f32 v6, v45, v73, -v7
	v_fmac_f32_e32 v2, v6, v6
	v_fma_f32 v7, v61, v73, -v9
	v_fmac_f32_e32 v2, v7, v7
	s_nop 1
	v_add_f32_dpp v2, v2, v2 row_ror:1 row_mask:0xf bank_mask:0xf
	s_nop 1
	v_add_f32_dpp v2, v2, v2 row_ror:2 row_mask:0xf bank_mask:0xf
	s_nop 1
	v_add_f32_dpp v2, v2, v2 row_ror:4 row_mask:0xf bank_mask:0xf
	s_nop 1
	v_add_f32_dpp v2, v2, v2 row_ror:8 row_mask:0xf bank_mask:0xf
	ds_swizzle_b32 v3, v2 offset:swizzle(SWAP,16)
	s_waitcnt lgkmcnt(0)
; __device__ __forceinline__ unsigned cvt_pk_bf16(float lo, float hi) { unsigned r; asm("v_cvt_pk_bf16_f32 %0, %1, %2" : "=v"(r) : "v"(lo), "v"(hi)); return r; }
; __device__ __forceinline__ float sum_row32(float v) { v += swz_xor<1>(v); v += swz_xor<2>(v); v += swz_xor<4>(v); v += swz_xor<8>(v); v += swz_xor<16>(v); return v; }
; __device__ __forceinline__ int crow(int r, int hi) { return (r & 3) + 8 * (r >> 2) + 4 * hi; }
; __device__ __forceinline__ void unitA(LAS char* lds, const gbf* PROJ, const gbf* VT, gbf* Y, const int S, const int tok0, const int h, const int qblk,
;                                       const float lam, const float oml, const gfl* subln, const float kn2a, const float kn2b, const int tid_) {
;     ...
;         for (int r = 0; r < 16; ++r) {
;             float ss = 0.f;
; #pragma unroll
;             for (int d = 0; d < 4; ++d) { const float v = o[d][r] * invr[r] - X[(d * 16 + r) * 64 + lane]; o[d][r] = v; ss += v * v; }
;             ss = sum_row32(ss);
;             const float rstd = __builtin_amdgcn_rsqf(ss * (1.f / 128.f) + EPS);
;             gbf* yp = Y + (size_t)(tok0 + q0 + crow(r, hi)) * DM + h * 128 + r32e;
; #pragma unroll
;             for (int d = 0; d < 4; ++d) yp[d * 32] = (bf16_t)(cvt_pk_bf16(o[d][r] * rstd * sub[d], 0.f) & 0xffffu);
;         }
	v_add_f32_e32 v2, v2, v3
	v_fmamk_f32 v2, v2, 0x3c000000, v218
	v_rsq_f32_e32 v8, v2
	v_or_b32_e32 v2, 19, v82
	v_ashrrev_i32_e32 v3, 31, v2
	v_lshlrev_b64 v[2:3], 11, v[2:3]
	v_mul_f32_e32 v4, v4, v8
	v_mul_f32_e32 v4, v0, v4
	v_lshl_add_u64 v[2:3], v[84:85], 0, v[2:3]
	v_cvt_pk_bf16_f32 v4, v4, v1
	global_store_short v[2:3], v4, off
	v_mul_f32_e32 v4, v5, v8
	v_mul_f32_e32 v4, v86, v4
	v_cvt_pk_bf16_f32 v4, v4, v1
	global_store_short v[2:3], v4, off offset:64
	v_mul_f32_e32 v4, v6, v8
	v_mul_f32_e32 v4, v87, v4
	v_cvt_pk_bf16_f32 v4, v4, v1
	global_store_short v[2:3], v4, off offset:128
	v_mul_f32_e32 v4, v7, v8
	v_mul_f32_e32 v4, v88, v4
	v_cvt_pk_bf16_f32 v4, v4, v1
	global_store_short v[2:3], v4, off offset:192
	ds_read2st64_b32 v[2:3], v89 offset0:12 offset1:13
	ds_read2st64_b32 v[4:5], v89 offset0:28 offset1:29
	ds_read2st64_b32 v[6:7], v89 offset0:44 offset1:45
	ds_read2st64_b32 v[8:9], v89 offset0:60 offset1:61
	s_waitcnt lgkmcnt(3)
	v_fma_f32 v2, v14, v66, -v2
	s_waitcnt lgkmcnt(2)
	v_fma_f32 v4, v30, v66, -v4
	v_mul_f32_e32 v10, v4, v4
	v_fmac_f32_e32 v10, v2, v2
	s_waitcnt lgkmcnt(1)
	v_fma_f32 v6, v46, v66, -v6
	v_fmac_f32_e32 v10, v6, v6
	s_waitcnt lgkmcnt(0)
	v_fma_f32 v8, v62, v66, -v8
	v_fmac_f32_e32 v10, v8, v8
	v_fma_f32 v5, v31, v67, -v5
	s_nop 1
	v_add_f32_dpp v10, v10, v10 row_ror:1 row_mask:0xf bank_mask:0xf
	s_nop 1
	v_add_f32_dpp v10, v10, v10 row_ror:2 row_mask:0xf bank_mask:0xf
	s_nop 1
	v_add_f32_dpp v10, v10, v10 row_ror:4 row_mask:0xf bank_mask:0xf
	s_nop 1
	v_add_f32_dpp v10, v10, v10 row_ror:8 row_mask:0xf bank_mask:0xf
	ds_swizzle_b32 v11, v10 offset:swizzle(SWAP,16)
	s_waitcnt lgkmcnt(0)
	v_add_f32_e32 v10, v10, v11
	v_fmamk_f32 v10, v10, 0x3c000000, v218
	v_rsq_f32_e32 v12, v10
	v_or_b32_e32 v10, 24, v82
	v_ashrrev_i32_e32 v11, 31, v10
	v_lshlrev_b64 v[10:11], 11, v[10:11]
	v_mul_f32_e32 v2, v2, v12
	v_mul_f32_e32 v2, v0, v2
	v_lshl_add_u64 v[10:11], v[84:85], 0, v[10:11]
	v_cvt_pk_bf16_f32 v2, v2, v1
	global_store_short v[10:11], v2, off
	v_mul_f32_e32 v2, v4, v12
	v_mul_f32_e32 v2, v86, v2
	v_cvt_pk_bf16_f32 v2, v2, v1
	global_store_short v[10:11], v2, off offset:64
	v_mul_f32_e32 v2, v6, v12
	v_mul_f32_e32 v2, v87, v2
	v_cvt_pk_bf16_f32 v2, v2, v1
	global_store_short v[10:11], v2, off offset:128
	v_mul_f32_e32 v2, v8, v12
	v_mul_f32_e32 v2, v88, v2
	v_cvt_pk_bf16_f32 v2, v2, v1
	global_store_short v[10:11], v2, off offset:192
	v_fma_f32 v4, v15, v67, -v3
	v_mul_f32_e32 v2, v5, v5
	v_fmac_f32_e32 v2, v4, v4
	v_fma_f32 v6, v47, v67, -v7
	v_fmac_f32_e32 v2, v6, v6
	v_fma_f32 v7, v63, v67, -v9
	v_fmac_f32_e32 v2, v7, v7
	s_nop 1
	v_add_f32_dpp v2, v2, v2 row_ror:1 row_mask:0xf bank_mask:0xf
	s_nop 1
	v_add_f32_dpp v2, v2, v2 row_ror:2 row_mask:0xf bank_mask:0xf
	s_nop 1
	v_add_f32_dpp v2, v2, v2 row_ror:4 row_mask:0xf bank_mask:0xf
	s_nop 1
	v_add_f32_dpp v2, v2, v2 row_ror:8 row_mask:0xf bank_mask:0xf
	ds_swizzle_b32 v3, v2 offset:swizzle(SWAP,16)
	s_waitcnt lgkmcnt(0)
	v_add_f32_e32 v2, v2, v3
	v_fmamk_f32 v2, v2, 0x3c000000, v218
	v_rsq_f32_e32 v8, v2
	v_or_b32_e32 v2, 25, v82
	v_ashrrev_i32_e32 v3, 31, v2
	v_lshlrev_b64 v[2:3], 11, v[2:3]
	v_mul_f32_e32 v4, v4, v8
	v_mul_f32_e32 v4, v0, v4
	v_lshl_add_u64 v[2:3], v[84:85], 0, v[2:3]
	v_cvt_pk_bf16_f32 v4, v4, v1
	global_store_short v[2:3], v4, off
	v_mul_f32_e32 v4, v5, v8
	v_mul_f32_e32 v4, v86, v4
	v_cvt_pk_bf16_f32 v4, v4, v1
	global_store_short v[2:3], v4, off offset:64
	v_mul_f32_e32 v4, v6, v8
	v_mul_f32_e32 v4, v87, v4
	v_cvt_pk_bf16_f32 v4, v4, v1
	global_store_short v[2:3], v4, off offset:128
	v_mul_f32_e32 v4, v7, v8
	v_mul_f32_e32 v4, v88, v4
	v_cvt_pk_bf16_f32 v4, v4, v1
	global_store_short v[2:3], v4, off offset:192
	ds_read2st64_b32 v[2:3], v89 offset0:14 offset1:15
	ds_read2st64_b32 v[4:5], v89 offset0:30 offset1:31
	ds_read2st64_b32 v[6:7], v89 offset0:46 offset1:47
	ds_read2st64_b32 v[8:9], v89 offset0:62 offset1:63
	s_waitcnt lgkmcnt(3)
	v_fma_f32 v2, v16, v68, -v2
	s_waitcnt lgkmcnt(2)
	v_fma_f32 v4, v32, v68, -v4
	v_mul_f32_e32 v10, v4, v4
	v_fmac_f32_e32 v10, v2, v2
	s_waitcnt lgkmcnt(1)
	v_fma_f32 v6, v48, v68, -v6
	v_fmac_f32_e32 v10, v6, v6
	s_waitcnt lgkmcnt(0)
	v_fma_f32 v8, v64, v68, -v8
	v_fmac_f32_e32 v10, v8, v8
	v_fma_f32 v5, v33, v69, -v5
	s_nop 1
	v_add_f32_dpp v10, v10, v10 row_ror:1 row_mask:0xf bank_mask:0xf
	s_nop 1
	v_add_f32_dpp v10, v10, v10 row_ror:2 row_mask:0xf bank_mask:0xf
	s_nop 1
	v_add_f32_dpp v10, v10, v10 row_ror:4 row_mask:0xf bank_mask:0xf
	s_nop 1
	v_add_f32_dpp v10, v10, v10 row_ror:8 row_mask:0xf bank_mask:0xf
	ds_swizzle_b32 v11, v10 offset:swizzle(SWAP,16)
	s_waitcnt lgkmcnt(0)
	v_add_f32_e32 v10, v10, v11
	v_fmamk_f32 v10, v10, 0x3c000000, v218
	v_rsq_f32_e32 v12, v10
	v_or_b32_e32 v10, 26, v82
	v_ashrrev_i32_e32 v11, 31, v10
	v_lshlrev_b64 v[10:11], 11, v[10:11]
	v_mul_f32_e32 v2, v2, v12
	v_mul_f32_e32 v2, v0, v2
	v_lshl_add_u64 v[10:11], v[84:85], 0, v[10:11]
	v_cvt_pk_bf16_f32 v2, v2, v1
	global_store_short v[10:11], v2, off
	v_mul_f32_e32 v2, v4, v12
	v_mul_f32_e32 v2, v86, v2
	v_cvt_pk_bf16_f32 v2, v2, v1
	global_store_short v[10:11], v2, off offset:64
	v_mul_f32_e32 v2, v6, v12
	v_mul_f32_e32 v2, v87, v2
	v_cvt_pk_bf16_f32 v2, v2, v1
	global_store_short v[10:11], v2, off offset:128
	v_mul_f32_e32 v2, v8, v12
	v_mul_f32_e32 v2, v88, v2
	v_cvt_pk_bf16_f32 v2, v2, v1
	global_store_short v[10:11], v2, off offset:192
	v_fma_f32 v4, v17, v69, -v3
	v_mul_f32_e32 v2, v5, v5
	v_fmac_f32_e32 v2, v4, v4
	v_fma_f32 v6, v49, v69, -v7
	v_fmac_f32_e32 v2, v6, v6
	v_fma_f32 v7, v65, v69, -v9
	v_fmac_f32_e32 v2, v7, v7
	s_nop 1
	v_add_f32_dpp v2, v2, v2 row_ror:1 row_mask:0xf bank_mask:0xf
	s_nop 1
	v_add_f32_dpp v2, v2, v2 row_ror:2 row_mask:0xf bank_mask:0xf
	s_nop 1
	v_add_f32_dpp v2, v2, v2 row_ror:4 row_mask:0xf bank_mask:0xf
	s_nop 1
	v_add_f32_dpp v2, v2, v2 row_ror:8 row_mask:0xf bank_mask:0xf
	ds_swizzle_b32 v3, v2 offset:swizzle(SWAP,16)
	s_waitcnt lgkmcnt(0)
	v_add_f32_e32 v2, v2, v3
	v_fmamk_f32 v2, v2, 0x3c000000, v218
	v_rsq_f32_e32 v8, v2
	v_or_b32_e32 v2, 27, v82
	v_ashrrev_i32_e32 v3, 31, v2
	v_lshlrev_b64 v[2:3], 11, v[2:3]
	v_mul_f32_e32 v4, v4, v8
	v_mul_f32_e32 v0, v0, v4
	v_lshl_add_u64 v[2:3], v[84:85], 0, v[2:3]
	v_cvt_pk_bf16_f32 v0, v0, v1
	global_store_short v[2:3], v0, off
	v_mul_f32_e32 v0, v5, v8
	v_mul_f32_e32 v0, v86, v0
	v_cvt_pk_bf16_f32 v0, v0, v1
	global_store_short v[2:3], v0, off offset:64
	v_mul_f32_e32 v0, v6, v8
	v_mul_f32_e32 v0, v87, v0
	v_cvt_pk_bf16_f32 v0, v0, v1
	global_store_short v[2:3], v0, off offset:128
	v_mul_f32_e32 v0, v7, v8
	v_mul_f32_e32 v0, v88, v0
	v_cvt_pk_bf16_f32 v0, v0, v1
	global_store_short v[2:3], v0, off offset:192
	s_branch .LBB0_358

; #define LAS __attribute__((address_space(3)))
; #define GAS __attribute__((address_space(1)))
; __device__ __forceinline__ int swap23(int r) { return (r & ~12) | ((r & 4) << 1) | ((r & 8) >> 1); }
; template <int NDV, bool MASK, int KPITCH, int VPITCH> ...
;     f32x16 s0, s1;
; #pragma unroll
;     for (int r = 0; r < 16; ++r) { s0[r] = 0.f; s1[r] = 0.f; }
; #pragma unroll
;     for (int dc = 0; dc < 4; ++dc) {
;         const bf16x8 a0 = *(const LAS bf16x8*)(kp + dc * 32);
;         const bf16x8 a1 = *(const LAS bf16x8*)(kp + 32 * KPITCH + dc * 32);
;         s0 = __builtin_amdgcn_mfma_f32_32x32x16_bf16(a0, qf[dc], s0, 0, 0, 0);
;         s1 = __builtin_amdgcn_mfma_f32_32x32x16_bf16(a1, qf[dc], s1, 0, 0, 0);
;     }
;     float mx = -3.0e38f;
; #pragma unroll
;     for (int r = 0; r < 16; ++r) {
;         const float c = (float)((r & 7) + 16 * (r >> 3));
;         const float d0 = __builtin_fabsf(dbase + c), d1 = __builtin_fabsf(dbase + (c + 32.f));
;         float t0 = __builtin_fmaf(nslope, d0, s0[r]), t1 = __builtin_fmaf(nslope, d1, s1[r]);
;         if (MASK) { t0 = d0 <= 128.f ? t0 : -1e30f; t1 = d1 <= 128.f ? t1 : -1e30f; }
;         s0[r] = t0; s1[r] = t1; mx = __builtin_fmaxf(mx, __builtin_fmaxf(t0, t1));
; __device__ __forceinline__ void unitB(LAS char* lds, const gbf* PROJ, const gbf* VT, gbf* Y, const int S, const int tok0, const int kvh, const int qblk, const gfl* sink, const int tid) {
;     ...
;     float mref = sink[hq] * LOG2E, lsum = hi == 0 ? 1.f : 0.f;
;     u32x4 kreg[5], vreg[5];
; #pragma unroll
;     for (int i = 0; i < 5; ++i) if (tlo + i <= thi) { kreg[i] = *(const GAS u32x4*)(ksrc + (size_t)((tlo + i) * 64) * NPROJ); vreg[i] = *(const GAS u32x4*)(vsrc + (tlo + i) * 64); }
; #pragma unroll
;     for (int i = 0; i < 5; ++i) if (tlo + i <= thi) { *(LAS u32x4*)(lds + i * B_BUF + kdst) = kreg[i]; *(LAS u32x4*)(lds + i * B_BUF + vdst) = vreg[i]; }
;     __syncthreads();
;     const int kpo = swap23(r32) * B_KP + hi * 16, vpo = B_KBYTES + r32 * B_VP + hi * 16;
;     const float qposf = (float)(q0 + r32 - 8 * hi);
;     for (int t = tlo; t <= thi; ++t) {
;         const int bo = (t - tlo) * B_BUF;
;         wave_tile<2, true, B_KP, B_VP>(lds + bo + kpo, lds + bo + vpo, qf, o, mref, lsum, (float)(t * 64) - qposf, nslope, wsf, r32, hi);
.LBB0_452:
	s_and_b32 s17, s40, 0x3fffffc0
	s_lshl_b32 s17, s17, 2
	s_add_i32 s22, s17, 0
	s_add_i32 s22, s22, 0x20000
	s_waitcnt vmcnt(0)
	v_mov_b32_e32 v33, 0
	s_and_b64 vcc, exec, s[20:21]
	v_lshl_add_u32 v85, v82, 2, s22
	v_mov_b32_e32 v32, 0
	v_mov_b32_e32 v31, 0
	v_mov_b32_e32 v30, 0
	v_mov_b32_e32 v29, 0
	v_mov_b32_e32 v28, 0
	v_mov_b32_e32 v27, 0
	v_mov_b32_e32 v26, 0
	v_mov_b32_e32 v25, 0
	v_mov_b32_e32 v24, 0
	v_mov_b32_e32 v23, 0
	v_mov_b32_e32 v22, 0
	v_mov_b32_e32 v21, 0
	v_mov_b32_e32 v20, 0
	v_mov_b32_e32 v19, 0
	v_mov_b32_e32 v18, 0
	v_mov_b32_e32 v17, 0
	v_mov_b32_e32 v16, 0
	v_mov_b32_e32 v15, 0
	v_mov_b32_e32 v14, 0
	v_mov_b32_e32 v13, 0
	v_mov_b32_e32 v12, 0
	v_mov_b32_e32 v11, 0
	v_mov_b32_e32 v10, 0
	v_mov_b32_e32 v9, 0
	v_mov_b32_e32 v8, 0
	v_mov_b32_e32 v7, 0
	v_mov_b32_e32 v6, 0
	v_mov_b32_e32 v5, 0
	v_mov_b32_e32 v4, 0
	v_mov_b32_e32 v3, 0
	v_mov_b32_e32 v2, 0
	v_mov_b32_e32 v87, v94
	s_waitcnt lgkmcnt(0)
	s_barrier
	s_cbranch_vccz .LBB0_461
	s_add_i32 s16, s16, 1
	v_mul_f32_e32 v120, 0x3fb8aa3b, v0
	v_cvt_f32_i32_e32 v0, s16
	v_add_u32_e32 v2, s39, v96
	v_cvt_f32_i32_e32 v89, v2
	v_mov_b32_e32 v2, v1
	v_exp_f32_e64 v0, -v0
	v_mov_b32_e32 v3, v1
	v_mov_b32_e32 v4, v1
	v_mov_b32_e32 v5, v1
	v_mov_b32_e32 v6, v1
	v_mov_b32_e32 v7, v1
	v_mov_b32_e32 v8, v1
	v_mov_b32_e32 v9, v1
	v_mov_b32_e32 v10, v1
	v_mov_b32_e32 v11, v1
	v_mov_b32_e32 v12, v1
	v_mov_b32_e32 v13, v1
	v_mov_b32_e32 v14, v1
	v_mov_b32_e32 v15, v1
	v_mov_b32_e32 v16, v1
	v_mov_b32_e32 v17, v1
	v_mov_b32_e32 v18, v1
	v_mov_b32_e32 v19, v1
	v_mov_b32_e32 v20, v1
	v_mov_b32_e32 v21, v1
	v_mov_b32_e32 v22, v1
	v_mov_b32_e32 v23, v1
	v_mov_b32_e32 v24, v1
	v_mov_b32_e32 v25, v1
	v_mov_b32_e32 v26, v1
	v_mov_b32_e32 v27, v1
	v_mov_b32_e32 v28, v1
	v_mov_b32_e32 v29, v1
	v_mov_b32_e32 v30, v1
	v_mov_b32_e32 v31, v1
	v_mul_f32_e32 v117, 0xbfb8aa3b, v0
	s_lshl_b32 s16, s38, 6
	v_mov_b32_e32 v0, v1
	v_mov_b64_e32 v[32:33], v[30:31]
	s_add_i32 s20, s38, -3
	s_add_i32 s21, s16, 0xffffff80
	v_mov_b32_e32 v118, v114
	v_mov_b32_e32 v119, v113
	v_mov_b64_e32 v[30:31], v[28:29]
	v_mov_b64_e32 v[28:29], v[26:27]
	v_mov_b64_e32 v[26:27], v[24:25]
	v_mov_b64_e32 v[24:25], v[22:23]
	v_mov_b64_e32 v[22:23], v[20:21]
	v_mov_b64_e32 v[20:21], v[18:19]
	v_mov_b64_e32 v[18:19], v[16:17]
	v_mov_b64_e32 v[16:17], v[14:15]
	v_mov_b64_e32 v[14:15], v[12:13]
	v_mov_b64_e32 v[12:13], v[10:11]
	v_mov_b64_e32 v[10:11], v[8:9]
	v_mov_b64_e32 v[8:9], v[6:7]
	v_mov_b64_e32 v[6:7], v[4:5]
	v_mov_b64_e32 v[4:5], v[2:3]
	v_mov_b64_e32 v[2:3], v[0:1]
	v_mov_b32_e32 v87, v94
	ds_read_b128 v[138:141], v118
	ds_read_b128 v[142:145], v118 offset:4608
	ds_read_b128 v[146:149], v118 offset:32
	ds_read_b128 v[150:153], v118 offset:4640
	ds_read_b128 v[154:157], v118 offset:64
	ds_read_b128 v[158:161], v118 offset:4672
	ds_read_b128 v[162:165], v118 offset:96
	ds_read_b128 v[166:169], v118 offset:4704
.LBB0_454:
	s_waitcnt lgkmcnt(0)
	ds_read_b128 v[170:173], v119
	ds_read_b128 v[174:177], v119 offset:4608
	ds_read_b128 v[178:181], v119 offset:32
	ds_read_b128 v[182:185], v119 offset:4640
	ds_read_b128 v[192:195], v119 offset:64
	ds_read_b128 v[196:199], v119 offset:4672
	ds_read_b128 v[200:203], v119 offset:96
	ds_read_b128 v[204:207], v119 offset:4704
	s_add_i32 s46, s21, 63
	s_cmp_lt_i32 s46, s39
	s_cselect_b64 s[48:49], -1, 0
	s_add_i32 s47, s39, 31
	s_cmp_gt_i32 s21, s47
	s_cselect_b64 s[50:51], -1, 0
	v_cvt_f32_i32_e32 v216, s21
	s_or_b64 s[52:53], s[48:49], s[50:51]
	v_sub_f32_e32 v216, v216, v89
	s_andn2_b64 vcc, exec, s[52:53]
	s_cbranch_vccnz .Lwb_t2
	v_cndmask_b32_e64 v212, -v117, v117, s[50:51]
	s_sub_i32 s54, s46, s39
	s_sub_i32 s55, s47, s21
	s_max_i32 s54, s54, s55
	v_fma_f32 v213, v212, v216, -v120
	v_mov_b32_e32 v34, v213
	v_fmamk_f32 v50, v212, 0x42000000, v213
	v_add_f32_e32 v35, v212, v213
	v_fmamk_f32 v51, v212, 0x42040000, v213
	v_fma_f32 v36, 2.0, v212, v213
	v_fmamk_f32 v52, v212, 0x42080000, v213
	v_fmamk_f32 v37, v212, 0x40400000, v213
	v_fmamk_f32 v53, v212, 0x420c0000, v213
	v_fma_f32 v38, 4.0, v212, v213
	v_fmamk_f32 v54, v212, 0x42100000, v213
	v_fmamk_f32 v39, v212, 0x40a00000, v213
	v_fmamk_f32 v55, v212, 0x42140000, v213
	v_fmamk_f32 v40, v212, 0x40c00000, v213
	v_fmamk_f32 v56, v212, 0x42180000, v213
	v_fmamk_f32 v41, v212, 0x40e00000, v213
	v_fmamk_f32 v57, v212, 0x421c0000, v213
	v_fmamk_f32 v42, v212, 0x41800000, v213
	v_fmamk_f32 v58, v212, 0x42400000, v213
	v_fmamk_f32 v43, v212, 0x41880000, v213
	v_fmamk_f32 v59, v212, 0x42440000, v213
	v_fmamk_f32 v44, v212, 0x41900000, v213
	v_fmamk_f32 v60, v212, 0x42480000, v213
	v_fmamk_f32 v45, v212, 0x41980000, v213
	v_fmamk_f32 v61, v212, 0x424c0000, v213
	v_fmamk_f32 v46, v212, 0x41a00000, v213
	v_fmamk_f32 v62, v212, 0x42500000, v213
	v_fmamk_f32 v47, v212, 0x41a80000, v213
	v_fmamk_f32 v63, v212, 0x42540000, v213
	v_fmamk_f32 v48, v212, 0x41b00000, v213
	v_fmamk_f32 v64, v212, 0x42580000, v213
	v_fmamk_f32 v49, v212, 0x41b80000, v213
	v_fmamk_f32 v65, v212, 0x425c0000, v213
	s_cmpk_gt_i32 s54, 0x80
	s_cbranch_scc0 .Lwb_qk
; template <int NDV, bool MASK, int KPITCH, int VPITCH> ...
;     ...
;     float mx = -3.0e38f;
; #pragma unroll
;     for (int r = 0; r < 16; ++r) {
;         const float c = (float)((r & 7) + 16 * (r >> 3));
;         const float d0 = __builtin_fabsf(dbase + c), d1 = __builtin_fabsf(dbase + (c + 32.f));
;         float t0 = __builtin_fmaf(nslope, d0, s0[r]), t1 = __builtin_fmaf(nslope, d1, s1[r]);
;         if (MASK) { t0 = d0 <= 128.f ? t0 : -1e30f; t1 = d1 <= 128.f ? t1 : -1e30f; }
;         s0[r] = t0; s1[r] = t1; mx = __builtin_fmaxf(mx, __builtin_fmaxf(t0, t1));
; template <int TYPE> ...
;     ...
;     if (TYPE == 2) {
; #pragma unroll
;         for (int r = 0; r < 16; ++r) { const float c = (float)((r & 7) + 16 * (r >> 3));
;             s0[r] = __builtin_fmaf(nslope, __builtin_fabsf(dbase + c), -mref); s1[r] = __builtin_fmaf(nslope, __builtin_fabsf(dbase + (c + 32.f)), -mref); }
	v_mov_b32_e32 v217, 0x43008000
	v_fma_f32 v217, v117, v217, -v120
	v_cmp_ge_f32_e64 s[56:57], v34, v217
	v_cmp_ge_f32_e64 s[58:59], v35, v217
	v_cmp_ge_f32_e64 s[60:61], v36, v217
	v_cmp_ge_f32_e64 s[62:63], v37, v217
	v_cndmask_b32_e64 v34, v229, v34, s[56:57]
	v_cndmask_b32_e64 v35, v229, v35, s[58:59]
	v_cndmask_b32_e64 v36, v229, v36, s[60:61]
	v_cndmask_b32_e64 v37, v229, v37, s[62:63]
	v_cmp_ge_f32_e64 s[56:57], v38, v217
	v_cmp_ge_f32_e64 s[58:59], v39, v217
	v_cmp_ge_f32_e64 s[60:61], v40, v217
	v_cmp_ge_f32_e64 s[62:63], v41, v217
	v_cndmask_b32_e64 v38, v229, v38, s[56:57]
	v_cndmask_b32_e64 v39, v229, v39, s[58:59]
	v_cndmask_b32_e64 v40, v229, v40, s[60:61]
	v_cndmask_b32_e64 v41, v229, v41, s[62:63]
	v_cmp_ge_f32_e64 s[56:57], v42, v217
	v_cmp_ge_f32_e64 s[58:59], v43, v217
	v_cmp_ge_f32_e64 s[60:61], v44, v217
	v_cmp_ge_f32_e64 s[62:63], v45, v217
	v_cndmask_b32_e64 v42, v229, v42, s[56:57]
	v_cndmask_b32_e64 v43, v229, v43, s[58:59]
	v_cndmask_b32_e64 v44, v229, v44, s[60:61]
	v_cndmask_b32_e64 v45, v229, v45, s[62:63]
	v_cmp_ge_f32_e64 s[56:57], v46, v217
	v_cmp_ge_f32_e64 s[58:59], v47, v217
	v_cmp_ge_f32_e64 s[60:61], v48, v217
	v_cmp_ge_f32_e64 s[62:63], v49, v217
	v_cndmask_b32_e64 v46, v229, v46, s[56:57]
	v_cndmask_b32_e64 v47, v229, v47, s[58:59]
	v_cndmask_b32_e64 v48, v229, v48, s[60:61]
	v_cndmask_b32_e64 v49, v229, v49, s[62:63]
	v_cmp_ge_f32_e64 s[56:57], v50, v217
	v_cmp_ge_f32_e64 s[58:59], v51, v217
	v_cmp_ge_f32_e64 s[60:61], v52, v217
	v_cmp_ge_f32_e64 s[62:63], v53, v217
	v_cndmask_b32_e64 v50, v229, v50, s[56:57]
	v_cndmask_b32_e64 v51, v229, v51, s[58:59]
	v_cndmask_b32_e64 v52, v229, v52, s[60:61]
	v_cndmask_b32_e64 v53, v229, v53, s[62:63]
	v_cmp_ge_f32_e64 s[56:57], v54, v217
	v_cmp_ge_f32_e64 s[58:59], v55, v217
	v_cmp_ge_f32_e64 s[60:61], v56, v217
	v_cmp_ge_f32_e64 s[62:63], v57, v217
	v_cndmask_b32_e64 v54, v229, v54, s[56:57]
	v_cndmask_b32_e64 v55, v229, v55, s[58:59]
	v_cndmask_b32_e64 v56, v229, v56, s[60:61]
	v_cndmask_b32_e64 v57, v229, v57, s[62:63]
	v_cmp_ge_f32_e64 s[56:57], v58, v217
	v_cmp_ge_f32_e64 s[58:59], v59, v217
	v_cmp_ge_f32_e64 s[60:61], v60, v217
	v_cmp_ge_f32_e64 s[62:63], v61, v217
	v_cndmask_b32_e64 v58, v229, v58, s[56:57]
	v_cndmask_b32_e64 v59, v229, v59, s[58:59]
	v_cndmask_b32_e64 v60, v229, v60, s[60:61]
	v_cndmask_b32_e64 v61, v229, v61, s[62:63]
	v_cmp_ge_f32_e64 s[56:57], v62, v217
	v_cmp_ge_f32_e64 s[58:59], v63, v217
	v_cmp_ge_f32_e64 s[60:61], v64, v217
	v_cmp_ge_f32_e64 s[62:63], v65, v217
	v_cndmask_b32_e64 v62, v229, v62, s[56:57]
	v_cndmask_b32_e64 v63, v229, v63, s[58:59]
	v_cndmask_b32_e64 v64, v229, v64, s[60:61]
	v_cndmask_b32_e64 v65, v229, v65, s[62:63]
	s_branch .Lwb_qk
.Lwb_t2:
	v_mov_b32_e32 v34, v216
	v_add_f32_e32 v50, 0x42000000, v216
	v_add_f32_e32 v35, 1.0, v216
	v_add_f32_e32 v51, 0x42040000, v216
	v_add_f32_e32 v36, 2.0, v216
	v_add_f32_e32 v52, 0x42080000, v216
	v_add_f32_e32 v37, 0x40400000, v216
	v_add_f32_e32 v53, 0x420c0000, v216
	v_add_f32_e32 v38, 4.0, v216
	v_add_f32_e32 v54, 0x42100000, v216
	v_add_f32_e32 v39, 0x40a00000, v216
	v_add_f32_e32 v55, 0x42140000, v216
	v_add_f32_e32 v40, 0x40c00000, v216
	v_add_f32_e32 v56, 0x42180000, v216
	v_add_f32_e32 v41, 0x40e00000, v216
	v_add_f32_e32 v57, 0x421c0000, v216
	v_add_f32_e32 v42, 0x41800000, v216
	v_add_f32_e32 v58, 0x42400000, v216
	v_add_f32_e32 v43, 0x41880000, v216
	v_add_f32_e32 v59, 0x42440000, v216
	v_add_f32_e32 v44, 0x41900000, v216
	v_add_f32_e32 v60, 0x42480000, v216
	v_add_f32_e32 v45, 0x41980000, v216
	v_add_f32_e32 v61, 0x424c0000, v216
	v_add_f32_e32 v46, 0x41a00000, v216
	v_add_f32_e32 v62, 0x42500000, v216
	v_add_f32_e32 v47, 0x41a80000, v216
	v_add_f32_e32 v63, 0x42540000, v216
	v_add_f32_e32 v48, 0x41b00000, v216
	v_add_f32_e32 v64, 0x42580000, v216
	v_add_f32_e32 v49, 0x41b80000, v216
	v_add_f32_e32 v65, 0x425c0000, v216
	v_fma_f32 v34, v117, |v34|, -v120
	v_fma_f32 v50, v117, |v50|, -v120
	v_fma_f32 v35, v117, |v35|, -v120
	v_fma_f32 v51, v117, |v51|, -v120
	v_fma_f32 v36, v117, |v36|, -v120
	v_fma_f32 v52, v117, |v52|, -v120
	v_fma_f32 v37, v117, |v37|, -v120
	v_fma_f32 v53, v117, |v53|, -v120
	v_fma_f32 v38, v117, |v38|, -v120
	v_fma_f32 v54, v117, |v54|, -v120
	v_fma_f32 v39, v117, |v39|, -v120
	v_fma_f32 v55, v117, |v55|, -v120
	v_fma_f32 v40, v117, |v40|, -v120
	v_fma_f32 v56, v117, |v56|, -v120
	v_fma_f32 v41, v117, |v41|, -v120
	v_fma_f32 v57, v117, |v57|, -v120
	v_fma_f32 v42, v117, |v42|, -v120
	v_fma_f32 v58, v117, |v58|, -v120
	v_fma_f32 v43, v117, |v43|, -v120
	v_fma_f32 v59, v117, |v59|, -v120
	v_fma_f32 v44, v117, |v44|, -v120
	v_fma_f32 v60, v117, |v60|, -v120
	v_fma_f32 v45, v117, |v45|, -v120
	v_fma_f32 v61, v117, |v61|, -v120
	v_fma_f32 v46, v117, |v46|, -v120
	v_fma_f32 v62, v117, |v62|, -v120
	v_fma_f32 v47, v117, |v47|, -v120
	v_fma_f32 v63, v117, |v63|, -v120
	v_fma_f32 v48, v117, |v48|, -v120
	v_fma_f32 v64, v117, |v64|, -v120
	v_fma_f32 v49, v117, |v49|, -v120
	v_fma_f32 v65, v117, |v65|, -v120
; template <int NDV, bool MASK, int KPITCH, int VPITCH> ...
;     ...
; #pragma unroll
;     for (int dc = 0; dc < 4; ++dc) {
;         const bf16x8 a0 = *(const LAS bf16x8*)(kp + dc * 32);
;         const bf16x8 a1 = *(const LAS bf16x8*)(kp + 32 * KPITCH + dc * 32);
;         s0 = __builtin_amdgcn_mfma_f32_32x32x16_bf16(a0, qf[dc], s0, 0, 0, 0);
;         s1 = __builtin_amdgcn_mfma_f32_32x32x16_bf16(a1, qf[dc], s1, 0, 0, 0);
;     }
;     float mx = -3.0e38f;
; #pragma unroll
;     for (int r = 0; r < 16; ++r) {
;         const float c = (float)((r & 7) + 16 * (r >> 3));
;         const float d0 = __builtin_fabsf(dbase + c), d1 = __builtin_fabsf(dbase + (c + 32.f));
;         float t0 = __builtin_fmaf(nslope, d0, s0[r]), t1 = __builtin_fmaf(nslope, d1, s1[r]);
;         if (MASK) { t0 = d0 <= 128.f ? t0 : -1e30f; t1 = d1 <= 128.f ? t1 : -1e30f; }
;         s0[r] = t0; s1[r] = t1; mx = __builtin_fmaxf(mx, __builtin_fmaxf(t0, t1));
;     }
;     mx = max_x32(mx);
;     if (__any(mx > mref + 8.f)) {
;         const float mnew = __builtin_fmaxf(mref, mx); const float alpha = __builtin_amdgcn_exp2f(mref - mnew);
;         lsum *= alpha; mref = mnew;
;         if (hi == 0) wsf[r32] = alpha;
; #pragma unroll
;         for (int r = 0; r < 16; ++r) { const float al = wsf[crow(r, hi)];
; #pragma unroll
;             for (int d = 0; d < NDV; ++d) o[d][r] *= al; }
;     }
;     float rs = 0.f;
; #pragma unroll
;     for (int r = 0; r < 16; ++r) { s0[r] = __builtin_amdgcn_exp2f(s0[r] - mref); s1[r] = __builtin_amdgcn_exp2f(s1[r] - mref); rs += s0[r] + s1[r]; }
;     lsum += rs;
;     bf16x8 pa[4];
;     { u32x4 w;
;       w.x = cvt_pk_bf16(s0[0], s0[1]); w.y = cvt_pk_bf16(s0[2], s0[3]); w.z = cvt_pk_bf16(s0[4], s0[5]); w.w = cvt_pk_bf16(s0[6], s0[7]); pa[0] = __builtin_bit_cast(bf16x8, w);
;       w.x = cvt_pk_bf16(s0[8], s0[9]); w.y = cvt_pk_bf16(s0[10], s0[11]); w.z = cvt_pk_bf16(s0[12], s0[13]); w.w = cvt_pk_bf16(s0[14], s0[15]); pa[1] = __builtin_bit_cast(bf16x8, w);
;       w.x = cvt_pk_bf16(s1[0], s1[1]); w.y = cvt_pk_bf16(s1[2], s1[3]); w.z = cvt_pk_bf16(s1[4], s1[5]); w.w = cvt_pk_bf16(s1[6], s1[7]); pa[2] = __builtin_bit_cast(bf16x8, w);
;       w.x = cvt_pk_bf16(s1[8], s1[9]); w.y = cvt_pk_bf16(s1[10], s1[11]); w.z = cvt_pk_bf16(s1[12], s1[13]); w.w = cvt_pk_bf16(s1[14], s1[15]); pa[3] = __builtin_bit_cast(bf16x8, w); }
; #pragma unroll
.Lwb_qk:
	s_nop 1
	v_mfma_f32_32x32x16_bf16 v[34:49], v[138:141], v[66:69], v[34:49]
	v_mfma_f32_32x32x16_bf16 v[50:65], v[142:145], v[66:69], v[50:65]
	ds_read_b128 v[138:141], v118 offset:18432
	ds_read_b128 v[142:145], v118 offset:23040
	v_mfma_f32_32x32x16_bf16 v[34:49], v[146:149], v[70:73], v[34:49]
	v_mfma_f32_32x32x16_bf16 v[50:65], v[150:153], v[70:73], v[50:65]
	ds_read_b128 v[146:149], v118 offset:18464
	ds_read_b128 v[150:153], v118 offset:23072
	v_mfma_f32_32x32x16_bf16 v[34:49], v[154:157], v[74:77], v[34:49]
	v_mfma_f32_32x32x16_bf16 v[50:65], v[158:161], v[74:77], v[50:65]
	ds_read_b128 v[154:157], v118 offset:18496
	ds_read_b128 v[158:161], v118 offset:23104
	v_mfma_f32_32x32x16_bf16 v[34:49], v[162:165], v[78:81], v[34:49]
	v_mfma_f32_32x32x16_bf16 v[50:65], v[166:169], v[78:81], v[50:65]
	s_waitcnt lgkmcnt(13)
	ds_read_b128 v[162:165], v118 offset:18528
	ds_read_b128 v[166:169], v118 offset:23136
	s_nop 9
	v_max3_f32 v212, v34, v35, v36
	v_max3_f32 v213, v50, v51, v52
	v_max3_f32 v212, v212, v37, v38
	v_max3_f32 v213, v213, v53, v54
	v_max3_f32 v212, v212, v39, v40
	v_max3_f32 v213, v213, v55, v56
	v_max3_f32 v212, v212, v41, v42
	v_max3_f32 v213, v213, v57, v58
	v_max3_f32 v212, v212, v43, v44
	v_max3_f32 v213, v213, v59, v60
	v_max3_f32 v212, v212, v45, v46
	v_max3_f32 v213, v213, v61, v62
	v_max3_f32 v212, v212, v47, v48
	v_max3_f32 v213, v213, v63, v64
	v_max3_f32 v212, v212, v49, v65
	v_max_f32_e32 v212, v212, v213
	v_mov_b32_e32 v213, v212
	s_nop 1
	v_permlane32_swap_b32_e32 v212, v213
	v_max_f32_e32 v212, v212, v213
	v_mov_b32_e32 v213, 0x41000000
	v_cmp_gt_f32_e32 vcc, v212, v213
	s_cbranch_vccz .Lwb_exp
	v_max_f32_e32 v212, 0, v212
	s_nop 0
	v_exp_f32_e64 v213, -v212
	s_and_saveexec_b64 s[16:17], s[6:7]
	ds_write_b32 v85, v213
	s_or_b64 exec, exec, s[16:17]
	v_mul_f32_e32 v87, v87, v213
	v_add_f32_e32 v120, v120, v212
	v_sub_f32_e32 v34, v34, v212
	v_sub_f32_e32 v50, v50, v212
	v_sub_f32_e32 v35, v35, v212
	v_sub_f32_e32 v51, v51, v212
	v_sub_f32_e32 v36, v36, v212
	v_sub_f32_e32 v52, v52, v212
	v_sub_f32_e32 v37, v37, v212
	v_sub_f32_e32 v53, v53, v212
	v_sub_f32_e32 v38, v38, v212
	v_sub_f32_e32 v54, v54, v212
	v_sub_f32_e32 v39, v39, v212
	v_sub_f32_e32 v55, v55, v212
	v_sub_f32_e32 v40, v40, v212
	v_sub_f32_e32 v56, v56, v212
	v_sub_f32_e32 v41, v41, v212
	v_sub_f32_e32 v57, v57, v212
	v_sub_f32_e32 v42, v42, v212
	v_sub_f32_e32 v58, v58, v212
	v_sub_f32_e32 v43, v43, v212
	v_sub_f32_e32 v59, v59, v212
	v_sub_f32_e32 v44, v44, v212
	v_sub_f32_e32 v60, v60, v212
	v_sub_f32_e32 v45, v45, v212
	v_sub_f32_e32 v61, v61, v212
	v_sub_f32_e32 v46, v46, v212
	v_sub_f32_e32 v62, v62, v212
	v_sub_f32_e32 v47, v47, v212
	v_sub_f32_e32 v63, v63, v212
	v_sub_f32_e32 v48, v48, v212
	v_sub_f32_e32 v64, v64, v212
	v_sub_f32_e32 v49, v49, v212
	v_sub_f32_e32 v65, v65, v212
	v_add_u32_e32 v121, s22, v95
	ds_read_b128 v[208:211], v121
	s_waitcnt lgkmcnt(0)
	v_pk_mul_f32 v[2:3], v[2:3], v[208:209]
	v_pk_mul_f32 v[4:5], v[4:5], v[210:211]
	v_pk_mul_f32 v[18:19], v[18:19], v[208:209]
	v_pk_mul_f32 v[20:21], v[20:21], v[210:211]
	ds_read_b128 v[208:211], v121 offset:32
	s_waitcnt lgkmcnt(0)
	v_pk_mul_f32 v[6:7], v[6:7], v[208:209]
	v_pk_mul_f32 v[8:9], v[8:9], v[210:211]
	v_pk_mul_f32 v[22:23], v[22:23], v[208:209]
	v_pk_mul_f32 v[24:25], v[24:25], v[210:211]
	ds_read_b128 v[208:211], v121 offset:64
	s_waitcnt lgkmcnt(0)
	v_pk_mul_f32 v[10:11], v[10:11], v[208:209]
	v_pk_mul_f32 v[12:13], v[12:13], v[210:211]
	v_pk_mul_f32 v[26:27], v[26:27], v[208:209]
	v_pk_mul_f32 v[28:29], v[28:29], v[210:211]
	ds_read_b128 v[208:211], v121 offset:96
	s_waitcnt lgkmcnt(0)
	v_pk_mul_f32 v[14:15], v[14:15], v[208:209]
	v_pk_mul_f32 v[16:17], v[16:17], v[210:211]
	v_pk_mul_f32 v[30:31], v[30:31], v[208:209]
	v_pk_mul_f32 v[32:33], v[32:33], v[210:211]
.Lwb_exp:
	v_exp_f32_e32 v34, v34
	v_exp_f32_e32 v35, v35
	v_exp_f32_e32 v36, v36
	v_add_f32_e32 v214, v34, v35
	v_exp_f32_e32 v37, v37
	v_add_f32_e32 v214, v214, v36
	v_exp_f32_e32 v38, v38
	v_add_f32_e32 v214, v214, v37
	v_exp_f32_e32 v39, v39
	v_add_f32_e32 v214, v214, v38
	v_exp_f32_e32 v40, v40
	v_add_f32_e32 v214, v214, v39
	v_exp_f32_e32 v41, v41
	v_add_f32_e32 v214, v214, v40
	v_cvt_pk_bf16_f32 v34, v34, v35
	v_add_f32_e32 v214, v214, v41
	v_cvt_pk_bf16_f32 v35, v36, v37
	v_cvt_pk_bf16_f32 v36, v38, v39
	v_cvt_pk_bf16_f32 v37, v40, v41
	s_waitcnt lgkmcnt(14)
	s_nop 0
	v_mfma_f32_32x32x16_bf16 v[2:17], v[34:37], v[170:173], v[2:17]
	v_exp_f32_e32 v42, v42
	v_exp_f32_e32 v43, v43
	v_add_f32_e32 v214, v214, v42
	v_exp_f32_e32 v44, v44
	v_add_f32_e32 v214, v214, v43
	v_exp_f32_e32 v45, v45
	v_add_f32_e32 v214, v214, v44
	v_exp_f32_e32 v46, v46
	v_add_f32_e32 v214, v214, v45
	v_exp_f32_e32 v47, v47
	v_mfma_f32_32x32x16_bf16 v[18:33], v[34:37], v[174:177], v[18:33]
	v_add_f32_e32 v214, v214, v46
	v_exp_f32_e32 v48, v48
	v_add_f32_e32 v214, v214, v47
	v_exp_f32_e32 v49, v49
	v_add_f32_e32 v214, v214, v48
	v_cvt_pk_bf16_f32 v42, v42, v43
	v_add_f32_e32 v214, v214, v49
	v_cvt_pk_bf16_f32 v43, v44, v45
	v_cvt_pk_bf16_f32 v44, v46, v47
	v_cvt_pk_bf16_f32 v45, v48, v49
	s_waitcnt lgkmcnt(12)
	s_nop 0
	v_mfma_f32_32x32x16_bf16 v[2:17], v[42:45], v[178:181], v[2:17]
	v_exp_f32_e32 v50, v50
	v_exp_f32_e32 v51, v51
	v_exp_f32_e32 v52, v52
	v_add_f32_e32 v215, v50, v51
	v_exp_f32_e32 v53, v53
	v_add_f32_e32 v215, v215, v52
	v_exp_f32_e32 v54, v54
	v_add_f32_e32 v215, v215, v53
	v_exp_f32_e32 v55, v55
	v_add_f32_e32 v215, v215, v54
	v_mfma_f32_32x32x16_bf16 v[18:33], v[42:45], v[182:185], v[18:33]
	v_exp_f32_e32 v56, v56
	v_add_f32_e32 v215, v215, v55
	v_exp_f32_e32 v57, v57
	v_add_f32_e32 v215, v215, v56
	v_cvt_pk_bf16_f32 v50, v50, v51
	v_add_f32_e32 v215, v215, v57
	v_cvt_pk_bf16_f32 v51, v52, v53
	v_cvt_pk_bf16_f32 v52, v54, v55
	v_cvt_pk_bf16_f32 v53, v56, v57
	s_waitcnt lgkmcnt(10)
	s_nop 0
	v_mfma_f32_32x32x16_bf16 v[2:17], v[50:53], v[192:195], v[2:17]
	v_exp_f32_e32 v58, v58
	v_exp_f32_e32 v59, v59
	v_add_f32_e32 v215, v215, v58
	v_exp_f32_e32 v60, v60
	v_add_f32_e32 v215, v215, v59
	v_exp_f32_e32 v61, v61
	v_add_f32_e32 v215, v215, v60
	v_exp_f32_e32 v62, v62
	v_add_f32_e32 v215, v215, v61
	v_exp_f32_e32 v63, v63
	v_mfma_f32_32x32x16_bf16 v[18:33], v[50:53], v[196:199], v[18:33]
	v_add_f32_e32 v215, v215, v62
	v_exp_f32_e32 v64, v64
	v_add_f32_e32 v215, v215, v63
	v_exp_f32_e32 v65, v65
	v_add_f32_e32 v215, v215, v64
	v_cvt_pk_bf16_f32 v58, v58, v59
	v_add_f32_e32 v215, v215, v65
	v_cvt_pk_bf16_f32 v59, v60, v61
	v_cvt_pk_bf16_f32 v60, v62, v63
	v_cvt_pk_bf16_f32 v61, v64, v65
	s_waitcnt lgkmcnt(8)
	s_nop 0
	v_mfma_f32_32x32x16_bf16 v[2:17], v[58:61], v[200:203], v[2:17]
	v_add_f32_e32 v214, v214, v215
	v_mfma_f32_32x32x16_bf16 v[18:33], v[58:61], v[204:207], v[18:33]
	v_add_f32_e32 v87, v87, v214
	s_add_i32 s20, s20, 1
	s_add_i32 s21, s21, 64
	v_add_u32_e32 v118, 0x4800, v118
	v_add_u32_e32 v119, 0x4800, v119
	s_cmp_ge_i32 s20, s37
	s_cbranch_scc1 .LBB0_461
	s_branch .LBB0_454
